# scan: hand-written column-oriented f32 solve (pk_fma, transposed MB), stage X/Y LDS read hoisting
# speedup vs baseline: 1.0228x; 1.0165x over previous
.LBB0_391:
	s_andn2_saveexec_b64 s[20:21], s[78:79]
	v_subrev_u32_e32 v19, 0x17900, v151
	v_lshrrev_b32_e32 v19, 4, v19
	v_lshl_add_u32 v19, v145, 4, v19
	v_add_u32_e32 v19, 0x17900, v19
	ds_write2_b32 v19, v14, v15 offset1:16
	ds_write2_b32 v19, v16, v17 offset0:32 offset1:48

.LBB0_395:
	s_cmp_lg_u32 s21, 0
	s_cbranch_scc0 .Lsx0_a
	s_add_i32 s24, s21, -16
	s_and_b64 s[2:3], s[12:13], exec
	s_cselect_b32 s2, s24, s19
	ds_read_b64 v[116:117], v190 offset:4096
	v_lshl_add_u32 v194, s2, 6, v183
	v_lshl_add_u64 v[118:119], v[194:195], 1, s[78:79]
.Lsx0_a:
	v_add_u32_e32 v192, v144, v145
	v_add_u32_e32 v199, v150, v145
	s_and_saveexec_b64 s[2:3], s[54:55]
	s_cbranch_execz .LBB0_401
	v_add_u32_e32 v22, v159, v153
	ds_read2st64_b32 v[28:29], v159 offset0:103 offset1:109
	ds_read2st64_b32 v[26:27], v22 offset0:96 offset1:97
	ds_read2st64_b32 v[24:25], v22 offset0:98 offset1:99
	ds_read2st64_b32 v[22:23], v22 offset0:100 offset1:101
	v_mov_b32_e32 v30, 0
	s_and_saveexec_b64 s[68:69], s[50:51]
	s_cbranch_execz .LBB0_400
	ds_read_b32 v30, v159 offset:24832
	s_waitcnt lgkmcnt(0)
	v_add_f32_e32 v30, 0, v30

.LBB0_401:
	s_or_b64 exec, exec, s[2:3]
	s_and_saveexec_b64 s[2:3], s[54:55]
	s_cbranch_execz .Lsx0_c
	s_cmp_lg_u32 s21, 0
	s_cbranch_scc0 .Lsx0_c
	s_waitcnt lgkmcnt(0)
	v_cvt_pk_bf16_f32 v120, v116, v117
	global_store_dword v[118:119], v120, off
.Lsx0_c:
	s_or_b64 exec, exec, s[2:3]
	v_mov_b32_e32 v22, 0
	v_mov_b32_e32 v23, 0
	v_mov_b32_e32 v24, 0
	v_mov_b32_e32 v25, 0
	s_and_saveexec_b64 s[2:3], s[56:57]
	s_cbranch_execz .LBB0_403
	ds_read_b128 v[48:51], v174
	ds_read_b128 v[60:63], v192 offset:49152
	ds_read_b128 v[52:55], v174 offset:64
	ds_read_b128 v[64:67], v192 offset:49216
	ds_read_b128 v[56:59], v175
	ds_read_b128 v[68:71], v199
	ds_read_b128 v[72:75], v192 offset:58368
	ds_read_b128 v[76:79], v192 offset:58432
	s_waitcnt lgkmcnt(6)
	v_mfma_f32_16x16x32_bf16 v[30:33], v[48:51], v[60:63], 0
	s_waitcnt lgkmcnt(4)
	v_mfma_f32_16x16x32_bf16 v[30:33], v[52:55], v[64:67], v[30:33]
	s_waitcnt lgkmcnt(2)
	v_mfma_f32_16x16x32_bf16 v[30:33], v[56:59], v[68:71], v[30:33]
	s_waitcnt lgkmcnt(1)
	v_mfma_f32_16x16x32_bf16 v[22:25], v[48:51], v[72:75], 0
	s_waitcnt lgkmcnt(0)
	v_mfma_f32_16x16x32_bf16 v[22:25], v[52:55], v[76:79], v[22:25]
	s_cmp_lg_u32 s21, 0
	s_cbranch_scc0 .Lsx0_d
	v_cvt_pk_bf16_f32 v120, v116, v117
	global_store_dword v[118:119], v120, off
.Lsx0_d:
	s_nop 3
	ds_write_b128 v176, v[30:33]
.LBB0_403:
	s_or_b64 exec, exec, s[2:3]
	s_waitcnt lgkmcnt(0)
	s_barrier
	v_add_u32_e32 v191, 0x17d00, v177
	s_and_saveexec_b64 s[2:3], s[48:49]
	s_cbranch_execz .LBB0_405
	s_setprio 3
	v_mov_b32_e32 v23, 0x17900
	ds_read2st64_b32 v[32:33], v191 offset0:0 offset1:1
	ds_read_b128 v[48:51], v23 offset:0
	ds_read2st64_b32 v[34:35], v191 offset0:2 offset1:3
	ds_read2st64_b32 v[36:37], v191 offset0:4 offset1:5
	ds_read_b128 v[52:55], v23 offset:16
	ds_read2st64_b32 v[38:39], v191 offset0:6 offset1:7
	ds_read2st64_b32 v[40:41], v191 offset0:8 offset1:9
	ds_read_b128 v[56:59], v23 offset:32
	ds_read2st64_b32 v[42:43], v191 offset0:10 offset1:11
	ds_read2st64_b32 v[44:45], v191 offset0:12 offset1:13
	ds_read_b128 v[60:63], v23 offset:48
	ds_read2st64_b32 v[46:47], v191 offset0:14 offset1:15
	ds_read_b128 v[64:67], v23 offset:64
	ds_read_b128 v[68:71], v23 offset:80
	ds_read_b128 v[72:75], v23 offset:96
	s_waitcnt lgkmcnt(13)
	v_fmac_f32_e32 v33, v49, v32
	s_waitcnt lgkmcnt(12)
	v_pk_fma_f32 v[34:35], v[50:51], v[32:33], v[34:35] op_sel_hi:[1,0,1]
	ds_read_b128 v[76:79], v23 offset:112
	s_waitcnt lgkmcnt(11)
	v_pk_fma_f32 v[36:37], v[52:53], v[32:33], v[36:37] op_sel_hi:[1,0,1]
	ds_read_b128 v[80:83], v23 offset:128
	ds_read_b128 v[84:87], v23 offset:144
	s_waitcnt lgkmcnt(12)
	v_pk_fma_f32 v[38:39], v[54:55], v[32:33], v[38:39] op_sel_hi:[1,0,1]
	ds_read_b128 v[88:91], v23 offset:160
	s_waitcnt lgkmcnt(11)
	v_pk_fma_f32 v[40:41], v[56:57], v[32:33], v[40:41] op_sel_hi:[1,0,1]
	ds_read_b128 v[92:95], v23 offset:176
	ds_read_b128 v[112:115], v23 offset:208
	s_waitcnt lgkmcnt(12)
	v_pk_fma_f32 v[42:43], v[58:59], v[32:33], v[42:43] op_sel_hi:[1,0,1]
	ds_read_b128 v[116:119], v23 offset:224
	s_waitcnt lgkmcnt(11)
	v_pk_fma_f32 v[44:45], v[60:61], v[32:33], v[44:45] op_sel_hi:[1,0,1]
	ds_read_b128 v[120:123], v23 offset:240
	ds_read_b128 v[124:127], v23 offset:272
	s_waitcnt lgkmcnt(12)
	v_pk_fma_f32 v[46:47], v[62:63], v[32:33], v[46:47] op_sel_hi:[1,0,1]
	ds_read_b128 v[128:131], v23 offset:288
	s_waitcnt lgkmcnt(12)
	v_pk_fma_f32 v[34:35], v[66:67], v[32:33], v[34:35] op_sel:[0,1,0] op_sel_hi:[1,1,1]
	ds_read_b128 v[132:135], v23 offset:304
	s_waitcnt lgkmcnt(12)
	v_pk_fma_f32 v[36:37], v[68:69], v[32:33], v[36:37] op_sel:[0,1,0] op_sel_hi:[1,1,1]
	ds_read_b128 v[204:207], v23 offset:336
	v_pk_fma_f32 v[38:39], v[70:71], v[32:33], v[38:39] op_sel:[0,1,0] op_sel_hi:[1,1,1]
	s_waitcnt lgkmcnt(12)
	v_pk_fma_f32 v[40:41], v[72:73], v[32:33], v[40:41] op_sel:[0,1,0] op_sel_hi:[1,1,1]
	ds_read_b128 v[208:211], v23 offset:352
	v_pk_fma_f32 v[42:43], v[74:75], v[32:33], v[42:43] op_sel:[0,1,0] op_sel_hi:[1,1,1]
	s_waitcnt lgkmcnt(12)
	v_pk_fma_f32 v[44:45], v[76:77], v[32:33], v[44:45] op_sel:[0,1,0] op_sel_hi:[1,1,1]
	ds_read_b128 v[212:215], v23 offset:368
	v_pk_fma_f32 v[46:47], v[78:79], v[32:33], v[46:47] op_sel:[0,1,0] op_sel_hi:[1,1,1]
	s_waitcnt lgkmcnt(12)
	v_fmac_f32_e32 v35, v83, v34
	ds_read_b128 v[216:219], v23 offset:400
	s_waitcnt lgkmcnt(12)
	v_pk_fma_f32 v[36:37], v[84:85], v[34:35], v[36:37] op_sel_hi:[1,0,1]
	ds_read_b128 v[228:231], v23 offset:416
	v_pk_fma_f32 v[38:39], v[86:87], v[34:35], v[38:39] op_sel_hi:[1,0,1]
	s_waitcnt lgkmcnt(12)
	v_pk_fma_f32 v[40:41], v[88:89], v[34:35], v[40:41] op_sel_hi:[1,0,1]
	ds_read_b128 v[232:235], v23 offset:432
	v_pk_fma_f32 v[42:43], v[90:91], v[34:35], v[42:43] op_sel_hi:[1,0,1]
	s_waitcnt lgkmcnt(12)
	v_pk_fma_f32 v[44:45], v[92:93], v[34:35], v[44:45] op_sel_hi:[1,0,1]
	ds_read_b128 v[48:51], v23 offset:480
	v_pk_fma_f32 v[46:47], v[94:95], v[34:35], v[46:47] op_sel_hi:[1,0,1]
	s_waitcnt lgkmcnt(12)
	v_pk_fma_f32 v[36:37], v[112:113], v[34:35], v[36:37] op_sel:[0,1,0] op_sel_hi:[1,1,1]
	ds_read_b128 v[52:55], v23 offset:496
	v_pk_fma_f32 v[38:39], v[114:115], v[34:35], v[38:39] op_sel:[0,1,0] op_sel_hi:[1,1,1]
	s_waitcnt lgkmcnt(12)
	v_pk_fma_f32 v[40:41], v[116:117], v[34:35], v[40:41] op_sel:[0,1,0] op_sel_hi:[1,1,1]
	ds_read_b128 v[56:59], v23 offset:544
	v_pk_fma_f32 v[42:43], v[118:119], v[34:35], v[42:43] op_sel:[0,1,0] op_sel_hi:[1,1,1]
	s_waitcnt lgkmcnt(12)
	v_pk_fma_f32 v[44:45], v[120:121], v[34:35], v[44:45] op_sel:[0,1,0] op_sel_hi:[1,1,1]
	ds_read_b128 v[60:63], v23 offset:560
	v_pk_fma_f32 v[46:47], v[122:123], v[34:35], v[46:47] op_sel:[0,1,0] op_sel_hi:[1,1,1]
	s_waitcnt lgkmcnt(12)
	v_fmac_f32_e32 v37, v125, v36
	ds_read_b128 v[64:67], v23 offset:608
	v_pk_fma_f32 v[38:39], v[126:127], v[36:37], v[38:39] op_sel_hi:[1,0,1]
	s_waitcnt lgkmcnt(12)
	v_pk_fma_f32 v[40:41], v[128:129], v[36:37], v[40:41] op_sel_hi:[1,0,1]
	ds_read_b128 v[68:71], v23 offset:624
	v_pk_fma_f32 v[42:43], v[130:131], v[36:37], v[42:43] op_sel_hi:[1,0,1]
	s_waitcnt lgkmcnt(12)
	v_pk_fma_f32 v[44:45], v[132:133], v[36:37], v[44:45] op_sel_hi:[1,0,1]
	ds_read_b128 v[72:75], v23 offset:672
	v_pk_fma_f32 v[46:47], v[134:135], v[36:37], v[46:47] op_sel_hi:[1,0,1]
	s_waitcnt lgkmcnt(12)
	v_pk_fma_f32 v[38:39], v[206:207], v[36:37], v[38:39] op_sel:[0,1,0] op_sel_hi:[1,1,1]
	ds_read_b128 v[76:79], v23 offset:688
	s_waitcnt lgkmcnt(12)
	v_pk_fma_f32 v[40:41], v[208:209], v[36:37], v[40:41] op_sel:[0,1,0] op_sel_hi:[1,1,1]
	ds_read_b128 v[80:83], v23 offset:752
	v_pk_fma_f32 v[42:43], v[210:211], v[36:37], v[42:43] op_sel:[0,1,0] op_sel_hi:[1,1,1]
	s_waitcnt lgkmcnt(12)
	v_pk_fma_f32 v[44:45], v[212:213], v[36:37], v[44:45] op_sel:[0,1,0] op_sel_hi:[1,1,1]
	ds_read_b128 v[84:87], v23 offset:816
	v_pk_fma_f32 v[46:47], v[214:215], v[36:37], v[46:47] op_sel:[0,1,0] op_sel_hi:[1,1,1]
	s_waitcnt lgkmcnt(12)
	v_fmac_f32_e32 v39, v219, v38
	ds_read_b128 v[88:91], v23 offset:880
	s_waitcnt lgkmcnt(12)
	v_pk_fma_f32 v[40:41], v[228:229], v[38:39], v[40:41] op_sel_hi:[1,0,1]
	ds_read_b128 v[92:95], v23 offset:944
	v_pk_fma_f32 v[42:43], v[230:231], v[38:39], v[42:43] op_sel_hi:[1,0,1]
	s_waitcnt lgkmcnt(12)
	v_pk_fma_f32 v[44:45], v[232:233], v[38:39], v[44:45] op_sel_hi:[1,0,1]
	v_pk_fma_f32 v[46:47], v[234:235], v[38:39], v[46:47] op_sel_hi:[1,0,1]
	s_waitcnt lgkmcnt(11)
	v_pk_fma_f32 v[40:41], v[48:49], v[38:39], v[40:41] op_sel:[0,1,0] op_sel_hi:[1,1,1]
	v_pk_fma_f32 v[42:43], v[50:51], v[38:39], v[42:43] op_sel:[0,1,0] op_sel_hi:[1,1,1]
	s_waitcnt lgkmcnt(10)
	v_pk_fma_f32 v[44:45], v[52:53], v[38:39], v[44:45] op_sel:[0,1,0] op_sel_hi:[1,1,1]
	v_pk_fma_f32 v[46:47], v[54:55], v[38:39], v[46:47] op_sel:[0,1,0] op_sel_hi:[1,1,1]
	s_waitcnt lgkmcnt(9)
	v_fmac_f32_e32 v41, v57, v40
	v_pk_fma_f32 v[42:43], v[58:59], v[40:41], v[42:43] op_sel_hi:[1,0,1]
	s_waitcnt lgkmcnt(8)
	v_pk_fma_f32 v[44:45], v[60:61], v[40:41], v[44:45] op_sel_hi:[1,0,1]
	v_pk_fma_f32 v[46:47], v[62:63], v[40:41], v[46:47] op_sel_hi:[1,0,1]
	s_waitcnt lgkmcnt(7)
	v_pk_fma_f32 v[42:43], v[66:67], v[40:41], v[42:43] op_sel:[0,1,0] op_sel_hi:[1,1,1]
	s_waitcnt lgkmcnt(6)
	v_pk_fma_f32 v[44:45], v[68:69], v[40:41], v[44:45] op_sel:[0,1,0] op_sel_hi:[1,1,1]
	v_pk_fma_f32 v[46:47], v[70:71], v[40:41], v[46:47] op_sel:[0,1,0] op_sel_hi:[1,1,1]
	s_waitcnt lgkmcnt(5)
	v_fmac_f32_e32 v43, v75, v42
	s_waitcnt lgkmcnt(4)
	v_pk_fma_f32 v[44:45], v[76:77], v[42:43], v[44:45] op_sel_hi:[1,0,1]
	v_pk_fma_f32 v[46:47], v[78:79], v[42:43], v[46:47] op_sel_hi:[1,0,1]
	s_waitcnt lgkmcnt(3)
	v_pk_fma_f32 v[44:45], v[80:81], v[42:43], v[44:45] op_sel:[0,1,0] op_sel_hi:[1,1,1]
	v_pk_fma_f32 v[46:47], v[82:83], v[42:43], v[46:47] op_sel:[0,1,0] op_sel_hi:[1,1,1]
	s_waitcnt lgkmcnt(2)
	v_fmac_f32_e32 v45, v85, v44
	v_pk_fma_f32 v[46:47], v[86:87], v[44:45], v[46:47] op_sel_hi:[1,0,1]
	s_waitcnt lgkmcnt(1)
	v_pk_fma_f32 v[46:47], v[90:91], v[44:45], v[46:47] op_sel:[0,1,0] op_sel_hi:[1,1,1]
	s_waitcnt lgkmcnt(0)
	v_fmac_f32_e32 v47, v95, v46
	v_cvt_pk_bf16_f32 v24, v32, v33
	v_cvt_pk_bf16_f32 v25, v34, v35
	v_cvt_pk_bf16_f32 v26, v36, v37
	v_cvt_pk_bf16_f32 v27, v38, v39
	v_cvt_pk_bf16_f32 v28, v40, v41
	v_cvt_pk_bf16_f32 v29, v42, v43
	v_cvt_pk_bf16_f32 v30, v44, v45
	v_cvt_pk_bf16_f32 v31, v46, v47
	ds_write_b128 v140, v[24:27]
	ds_write_b128 v140, v[28:31] offset:16
	s_setprio 0

.LBB0_420:
	s_andn2_saveexec_b64 s[68:69], s[74:75]
	v_subrev_u32_e32 v26, 0x17900, v151
	v_lshrrev_b32_e32 v26, 4, v26
	v_lshl_add_u32 v26, v145, 4, v26
	v_add_u32_e32 v26, 0x17900, v26
	ds_write2_b32 v26, v22, v23 offset1:16
	ds_write2_b32 v26, v24, v25 offset0:32 offset1:48

.LBB0_426:
	s_add_i32 s24, s19, -16
	s_and_b64 s[2:3], s[12:13], exec
	s_waitcnt lgkmcnt(0)
	s_barrier
	s_cselect_b32 s2, s21, s24
	s_cmpk_lt_u32 s20, 0x7f
	ds_read_b64 v[116:117], v190
	v_lshl_add_u32 v194, s2, 6, v183
	s_cselect_b64 s[2:3], -1, 0
	v_lshl_add_u64 v[118:119], v[194:195], 1, s[78:79]
	s_and_b64 s[68:69], s[54:55], s[2:3]
	s_and_saveexec_b64 s[74:75], s[68:69]
	s_cbranch_execz .LBB0_430
	ds_read2st64_b32 v[28:29], v142 offset0:7 offset1:13
	ds_read2st64_b32 v[26:27], v185 offset1:1
	ds_read2st64_b32 v[24:25], v185 offset0:2 offset1:3
	ds_read2st64_b32 v[22:23], v185 offset0:4 offset1:5
	v_mov_b32_e32 v30, 0
	s_and_saveexec_b64 s[68:69], s[50:51]
	s_cbranch_execz .LBB0_429
	ds_read_b32 v30, v142 offset:256
	s_waitcnt lgkmcnt(0)
	v_add_f32_e32 v30, 0, v30

.LBB0_430:
	s_or_b64 exec, exec, s[74:75]
	s_and_saveexec_b64 s[74:75], s[54:55]
	s_cbranch_execz .Lsx1_c
	s_waitcnt lgkmcnt(0)
	v_cvt_pk_bf16_f32 v120, v116, v117
	global_store_dword v[118:119], v120, off
.Lsx1_c:
	s_or_b64 exec, exec, s[74:75]
	v_mov_b32_e32 v22, 0
	v_mov_b32_e32 v23, 0
	v_mov_b32_e32 v24, 0
	v_mov_b32_e32 v25, 0
	s_and_saveexec_b64 s[74:75], s[56:57]
	s_cbranch_execz .LBB0_432
	ds_read_b128 v[48:51], v174
	ds_read_b128 v[60:63], v192 offset:51456
	ds_read_b128 v[52:55], v174 offset:64
	ds_read_b128 v[64:67], v192 offset:51520
	ds_read_b128 v[56:59], v175 offset:5120
	ds_read_b128 v[68:71], v199
	ds_read_b128 v[72:75], v192 offset:60672
	ds_read_b128 v[76:79], v192 offset:60736
	s_waitcnt lgkmcnt(6)
	v_mfma_f32_16x16x32_bf16 v[30:33], v[48:51], v[60:63], 0
	s_waitcnt lgkmcnt(4)
	v_mfma_f32_16x16x32_bf16 v[30:33], v[52:55], v[64:67], v[30:33]
	s_waitcnt lgkmcnt(2)
	v_mfma_f32_16x16x32_bf16 v[30:33], v[56:59], v[68:71], v[30:33]
	s_waitcnt lgkmcnt(1)
	v_mfma_f32_16x16x32_bf16 v[22:25], v[48:51], v[72:75], 0
	s_waitcnt lgkmcnt(0)
	v_mfma_f32_16x16x32_bf16 v[22:25], v[52:55], v[76:79], v[22:25]
	v_cvt_pk_bf16_f32 v120, v116, v117
	global_store_dword v[118:119], v120, off
	s_nop 3
	ds_write_b128 v176, v[30:33]
.LBB0_432:
	s_or_b64 exec, exec, s[74:75]
	s_waitcnt lgkmcnt(0)
	s_barrier
	s_and_saveexec_b64 s[74:75], s[48:49]
	s_cbranch_execz .LBB0_434
	s_setprio 3
	v_mov_b32_e32 v23, 0x17900
	ds_read2st64_b32 v[32:33], v191 offset0:0 offset1:1
	ds_read_b128 v[48:51], v23 offset:0
	ds_read2st64_b32 v[34:35], v191 offset0:2 offset1:3
	ds_read2st64_b32 v[36:37], v191 offset0:4 offset1:5
	ds_read_b128 v[52:55], v23 offset:16
	ds_read2st64_b32 v[38:39], v191 offset0:6 offset1:7
	ds_read2st64_b32 v[40:41], v191 offset0:8 offset1:9
	ds_read_b128 v[56:59], v23 offset:32
	ds_read2st64_b32 v[42:43], v191 offset0:10 offset1:11
	ds_read2st64_b32 v[44:45], v191 offset0:12 offset1:13
	ds_read_b128 v[60:63], v23 offset:48
	ds_read2st64_b32 v[46:47], v191 offset0:14 offset1:15
	ds_read_b128 v[64:67], v23 offset:64
	ds_read_b128 v[68:71], v23 offset:80
	ds_read_b128 v[72:75], v23 offset:96
	s_waitcnt lgkmcnt(13)
	v_fmac_f32_e32 v33, v49, v32
	s_waitcnt lgkmcnt(12)
	v_pk_fma_f32 v[34:35], v[50:51], v[32:33], v[34:35] op_sel_hi:[1,0,1]
	ds_read_b128 v[76:79], v23 offset:112
	s_waitcnt lgkmcnt(11)
	v_pk_fma_f32 v[36:37], v[52:53], v[32:33], v[36:37] op_sel_hi:[1,0,1]
	ds_read_b128 v[80:83], v23 offset:128
	ds_read_b128 v[84:87], v23 offset:144
	s_waitcnt lgkmcnt(12)
	v_pk_fma_f32 v[38:39], v[54:55], v[32:33], v[38:39] op_sel_hi:[1,0,1]
	ds_read_b128 v[88:91], v23 offset:160
	s_waitcnt lgkmcnt(11)
	v_pk_fma_f32 v[40:41], v[56:57], v[32:33], v[40:41] op_sel_hi:[1,0,1]
	ds_read_b128 v[92:95], v23 offset:176
	ds_read_b128 v[112:115], v23 offset:208
	s_waitcnt lgkmcnt(12)
	v_pk_fma_f32 v[42:43], v[58:59], v[32:33], v[42:43] op_sel_hi:[1,0,1]
	ds_read_b128 v[116:119], v23 offset:224
	s_waitcnt lgkmcnt(11)
	v_pk_fma_f32 v[44:45], v[60:61], v[32:33], v[44:45] op_sel_hi:[1,0,1]
	ds_read_b128 v[120:123], v23 offset:240
	ds_read_b128 v[124:127], v23 offset:272
	s_waitcnt lgkmcnt(12)
	v_pk_fma_f32 v[46:47], v[62:63], v[32:33], v[46:47] op_sel_hi:[1,0,1]
	ds_read_b128 v[128:131], v23 offset:288
	s_waitcnt lgkmcnt(12)
	v_pk_fma_f32 v[34:35], v[66:67], v[32:33], v[34:35] op_sel:[0,1,0] op_sel_hi:[1,1,1]
	ds_read_b128 v[132:135], v23 offset:304
	s_waitcnt lgkmcnt(12)
	v_pk_fma_f32 v[36:37], v[68:69], v[32:33], v[36:37] op_sel:[0,1,0] op_sel_hi:[1,1,1]
	ds_read_b128 v[204:207], v23 offset:336
	v_pk_fma_f32 v[38:39], v[70:71], v[32:33], v[38:39] op_sel:[0,1,0] op_sel_hi:[1,1,1]
	s_waitcnt lgkmcnt(12)
	v_pk_fma_f32 v[40:41], v[72:73], v[32:33], v[40:41] op_sel:[0,1,0] op_sel_hi:[1,1,1]
	ds_read_b128 v[208:211], v23 offset:352
	v_pk_fma_f32 v[42:43], v[74:75], v[32:33], v[42:43] op_sel:[0,1,0] op_sel_hi:[1,1,1]
	s_waitcnt lgkmcnt(12)
	v_pk_fma_f32 v[44:45], v[76:77], v[32:33], v[44:45] op_sel:[0,1,0] op_sel_hi:[1,1,1]
	ds_read_b128 v[212:215], v23 offset:368
	v_pk_fma_f32 v[46:47], v[78:79], v[32:33], v[46:47] op_sel:[0,1,0] op_sel_hi:[1,1,1]
	s_waitcnt lgkmcnt(12)
	v_fmac_f32_e32 v35, v83, v34
	ds_read_b128 v[216:219], v23 offset:400
	s_waitcnt lgkmcnt(12)
	v_pk_fma_f32 v[36:37], v[84:85], v[34:35], v[36:37] op_sel_hi:[1,0,1]
	ds_read_b128 v[228:231], v23 offset:416
	v_pk_fma_f32 v[38:39], v[86:87], v[34:35], v[38:39] op_sel_hi:[1,0,1]
	s_waitcnt lgkmcnt(12)
	v_pk_fma_f32 v[40:41], v[88:89], v[34:35], v[40:41] op_sel_hi:[1,0,1]
	ds_read_b128 v[232:235], v23 offset:432
	v_pk_fma_f32 v[42:43], v[90:91], v[34:35], v[42:43] op_sel_hi:[1,0,1]
	s_waitcnt lgkmcnt(12)
	v_pk_fma_f32 v[44:45], v[92:93], v[34:35], v[44:45] op_sel_hi:[1,0,1]
	ds_read_b128 v[48:51], v23 offset:480
	v_pk_fma_f32 v[46:47], v[94:95], v[34:35], v[46:47] op_sel_hi:[1,0,1]
	s_waitcnt lgkmcnt(12)
	v_pk_fma_f32 v[36:37], v[112:113], v[34:35], v[36:37] op_sel:[0,1,0] op_sel_hi:[1,1,1]
	ds_read_b128 v[52:55], v23 offset:496
	v_pk_fma_f32 v[38:39], v[114:115], v[34:35], v[38:39] op_sel:[0,1,0] op_sel_hi:[1,1,1]
	s_waitcnt lgkmcnt(12)
	v_pk_fma_f32 v[40:41], v[116:117], v[34:35], v[40:41] op_sel:[0,1,0] op_sel_hi:[1,1,1]
	ds_read_b128 v[56:59], v23 offset:544
	v_pk_fma_f32 v[42:43], v[118:119], v[34:35], v[42:43] op_sel:[0,1,0] op_sel_hi:[1,1,1]
	s_waitcnt lgkmcnt(12)
	v_pk_fma_f32 v[44:45], v[120:121], v[34:35], v[44:45] op_sel:[0,1,0] op_sel_hi:[1,1,1]
	ds_read_b128 v[60:63], v23 offset:560
	v_pk_fma_f32 v[46:47], v[122:123], v[34:35], v[46:47] op_sel:[0,1,0] op_sel_hi:[1,1,1]
	s_waitcnt lgkmcnt(12)
	v_fmac_f32_e32 v37, v125, v36
	ds_read_b128 v[64:67], v23 offset:608
	v_pk_fma_f32 v[38:39], v[126:127], v[36:37], v[38:39] op_sel_hi:[1,0,1]
	s_waitcnt lgkmcnt(12)
	v_pk_fma_f32 v[40:41], v[128:129], v[36:37], v[40:41] op_sel_hi:[1,0,1]
	ds_read_b128 v[68:71], v23 offset:624
	v_pk_fma_f32 v[42:43], v[130:131], v[36:37], v[42:43] op_sel_hi:[1,0,1]
	s_waitcnt lgkmcnt(12)
	v_pk_fma_f32 v[44:45], v[132:133], v[36:37], v[44:45] op_sel_hi:[1,0,1]
	ds_read_b128 v[72:75], v23 offset:672
	v_pk_fma_f32 v[46:47], v[134:135], v[36:37], v[46:47] op_sel_hi:[1,0,1]
	s_waitcnt lgkmcnt(12)
	v_pk_fma_f32 v[38:39], v[206:207], v[36:37], v[38:39] op_sel:[0,1,0] op_sel_hi:[1,1,1]
	ds_read_b128 v[76:79], v23 offset:688
	s_waitcnt lgkmcnt(12)
	v_pk_fma_f32 v[40:41], v[208:209], v[36:37], v[40:41] op_sel:[0,1,0] op_sel_hi:[1,1,1]
	ds_read_b128 v[80:83], v23 offset:752
	v_pk_fma_f32 v[42:43], v[210:211], v[36:37], v[42:43] op_sel:[0,1,0] op_sel_hi:[1,1,1]
	s_waitcnt lgkmcnt(12)
	v_pk_fma_f32 v[44:45], v[212:213], v[36:37], v[44:45] op_sel:[0,1,0] op_sel_hi:[1,1,1]
	ds_read_b128 v[84:87], v23 offset:816
	v_pk_fma_f32 v[46:47], v[214:215], v[36:37], v[46:47] op_sel:[0,1,0] op_sel_hi:[1,1,1]
	s_waitcnt lgkmcnt(12)
	v_fmac_f32_e32 v39, v219, v38
	ds_read_b128 v[88:91], v23 offset:880
	s_waitcnt lgkmcnt(12)
	v_pk_fma_f32 v[40:41], v[228:229], v[38:39], v[40:41] op_sel_hi:[1,0,1]
	ds_read_b128 v[92:95], v23 offset:944
	v_pk_fma_f32 v[42:43], v[230:231], v[38:39], v[42:43] op_sel_hi:[1,0,1]
	s_waitcnt lgkmcnt(12)
	v_pk_fma_f32 v[44:45], v[232:233], v[38:39], v[44:45] op_sel_hi:[1,0,1]
	v_pk_fma_f32 v[46:47], v[234:235], v[38:39], v[46:47] op_sel_hi:[1,0,1]
	s_waitcnt lgkmcnt(11)
	v_pk_fma_f32 v[40:41], v[48:49], v[38:39], v[40:41] op_sel:[0,1,0] op_sel_hi:[1,1,1]
	v_pk_fma_f32 v[42:43], v[50:51], v[38:39], v[42:43] op_sel:[0,1,0] op_sel_hi:[1,1,1]
	s_waitcnt lgkmcnt(10)
	v_pk_fma_f32 v[44:45], v[52:53], v[38:39], v[44:45] op_sel:[0,1,0] op_sel_hi:[1,1,1]
	v_pk_fma_f32 v[46:47], v[54:55], v[38:39], v[46:47] op_sel:[0,1,0] op_sel_hi:[1,1,1]
	s_waitcnt lgkmcnt(9)
	v_fmac_f32_e32 v41, v57, v40
	v_pk_fma_f32 v[42:43], v[58:59], v[40:41], v[42:43] op_sel_hi:[1,0,1]
	s_waitcnt lgkmcnt(8)
	v_pk_fma_f32 v[44:45], v[60:61], v[40:41], v[44:45] op_sel_hi:[1,0,1]
	v_pk_fma_f32 v[46:47], v[62:63], v[40:41], v[46:47] op_sel_hi:[1,0,1]
	s_waitcnt lgkmcnt(7)
	v_pk_fma_f32 v[42:43], v[66:67], v[40:41], v[42:43] op_sel:[0,1,0] op_sel_hi:[1,1,1]
	s_waitcnt lgkmcnt(6)
	v_pk_fma_f32 v[44:45], v[68:69], v[40:41], v[44:45] op_sel:[0,1,0] op_sel_hi:[1,1,1]
	v_pk_fma_f32 v[46:47], v[70:71], v[40:41], v[46:47] op_sel:[0,1,0] op_sel_hi:[1,1,1]
	s_waitcnt lgkmcnt(5)
	v_fmac_f32_e32 v43, v75, v42
	s_waitcnt lgkmcnt(4)
	v_pk_fma_f32 v[44:45], v[76:77], v[42:43], v[44:45] op_sel_hi:[1,0,1]
	v_pk_fma_f32 v[46:47], v[78:79], v[42:43], v[46:47] op_sel_hi:[1,0,1]
	s_waitcnt lgkmcnt(3)
	v_pk_fma_f32 v[44:45], v[80:81], v[42:43], v[44:45] op_sel:[0,1,0] op_sel_hi:[1,1,1]
	v_pk_fma_f32 v[46:47], v[82:83], v[42:43], v[46:47] op_sel:[0,1,0] op_sel_hi:[1,1,1]
	s_waitcnt lgkmcnt(2)
	v_fmac_f32_e32 v45, v85, v44
	v_pk_fma_f32 v[46:47], v[86:87], v[44:45], v[46:47] op_sel_hi:[1,0,1]
	s_waitcnt lgkmcnt(1)
	v_pk_fma_f32 v[46:47], v[90:91], v[44:45], v[46:47] op_sel:[0,1,0] op_sel_hi:[1,1,1]
	s_waitcnt lgkmcnt(0)
	v_fmac_f32_e32 v47, v95, v46
	v_cvt_pk_bf16_f32 v24, v32, v33
	v_cvt_pk_bf16_f32 v25, v34, v35
	v_cvt_pk_bf16_f32 v26, v36, v37
	v_cvt_pk_bf16_f32 v27, v38, v39
	v_cvt_pk_bf16_f32 v28, v40, v41
	v_cvt_pk_bf16_f32 v29, v42, v43
	v_cvt_pk_bf16_f32 v30, v44, v45
	v_cvt_pk_bf16_f32 v31, v46, v47
	ds_write_b128 v140, v[24:27] offset:5120
	ds_write_b128 v140, v[28:31] offset:5136
	s_setprio 0

.LBB0_449:
	s_andn2_saveexec_b64 s[24:25], s[74:75]
	v_subrev_u32_e32 v26, 0x17900, v151
	v_lshrrev_b32_e32 v26, 4, v26
	v_lshl_add_u32 v26, v145, 4, v26
	v_add_u32_e32 v26, 0x17900, v26
	ds_write2_b32 v26, v22, v23 offset1:16
	ds_write2_b32 v26, v24, v25 offset0:32 offset1:48
